# baseline (speedup 1.0000x reference)
.LBB0_470:
	s_or_b64 exec, exec, s[0:1]
	s_mov_b32 s0, 0x8000
	v_cmp_gt_i32_e32 vcc, s0, v2
	s_and_saveexec_b64 s[0:1], vcc
	s_cbranch_execz .LBB0_475
	v_mbcnt_lo_u32_b32 v1, -1, 0
	v_mbcnt_hi_u32_b32 v4, -1, v1
	v_and_b32_e32 v1, 64, v4
	v_add_u32_e32 v5, 64, v1
	v_xor_b32_e32 v1, 32, v4
	v_cmp_lt_i32_e32 vcc, v1, v5
	v_xor_b32_e32 v6, 16, v4
	v_and_b32_e32 v3, 63, v106
	v_cndmask_b32_e32 v1, v4, v1, vcc
	v_cmp_lt_i32_e32 vcc, v6, v5
	v_mov_b32_e32 v13, 0
	v_readlane_b32 s16, v254, 24
	v_cndmask_b32_e32 v6, v4, v6, vcc
	v_lshlrev_b32_e32 v16, 2, v6
	v_xor_b32_e32 v6, 8, v4
	v_cmp_lt_i32_e32 vcc, v6, v5
	v_lshlrev_b32_e32 v12, 2, v3
	v_readlane_b32 s2, v254, 0
	v_cndmask_b32_e32 v6, v4, v6, vcc
	v_lshlrev_b32_e32 v17, 2, v6
	v_xor_b32_e32 v6, 4, v4
	v_cmp_lt_i32_e32 vcc, v6, v5
	v_lshlrev_b32_e32 v8, 4, v3
	v_mov_b32_e32 v9, v13
	v_cndmask_b32_e32 v6, v4, v6, vcc
	s_waitcnt vmcnt(17)
	v_lshlrev_b32_e32 v18, 2, v6
	v_xor_b32_e32 v6, 2, v4
	v_cmp_lt_i32_e32 vcc, v6, v5
	v_readlane_b32 s17, v254, 25
	v_readlane_b32 s18, v254, 26
	v_cndmask_b32_e32 v6, v4, v6, vcc
	v_lshlrev_b32_e32 v19, 2, v6
	v_xor_b32_e32 v6, 1, v4
	v_cmp_lt_i32_e32 vcc, v6, v5
	v_readlane_b32 s19, v254, 27
	v_readlane_b32 s20, v254, 28
	v_cndmask_b32_e32 v4, v4, v6, vcc
	v_readlane_b32 s21, v254, 29
	v_lshlrev_b32_e32 v10, 3, v3
	v_mov_b32_e32 v11, v13
	v_cmp_eq_u32_e64 s[4:5], 0, v3
	s_lshl_b32 s12, s2, 2
	v_lshlrev_b32_e32 v1, 2, v1
	v_lshlrev_b32_e32 v20, 2, v4
	v_lshl_add_u64 v[4:5], s[16:17], 0, v[8:9]
	v_lshl_add_u64 v[6:7], s[18:19], 0, v[8:9]
	v_lshl_add_u64 v[8:9], s[82:83], 0, v[8:9]
	v_lshl_add_u64 v[10:11], s[20:21], 0, v[10:11]
	v_lshl_add_u64 v[12:13], s[94:95], 0, v[12:13]
	s_mov_b64 s[10:11], 0
	v_mov_b32_e32 v21, 0x3727c5ac
	s_mov_b32 s13, 0x800000
	s_mov_b32 s14, 0x42fe0000
	s_mov_b32 s15, 0x40c0c00
	s_movk_i32 s16, 0x7fff
	v_readlane_b32 s3, v254, 1
	v_readlane_b32 s22, v254, 30
	v_readlane_b32 s23, v254, 31
	v_readlane_b32 s24, v254, 32
	v_readlane_b32 s25, v254, 33
	v_readlane_b32 s26, v254, 34
	v_readlane_b32 s27, v254, 35
	v_readlane_b32 s28, v254, 36
	v_readlane_b32 s29, v254, 37
	v_readlane_b32 s30, v254, 38
	v_readlane_b32 s31, v254, 39
	global_load_dwordx4 v[200:203], v[4:5], off
	global_load_dwordx4 v[204:207], v[6:7], off
	global_load_dwordx4 v[208:211], v[4:5], off offset:1024
	global_load_dwordx4 v[212:215], v[6:7], off offset:1024
	global_load_dwordx4 v[216:219], v[4:5], off offset:2048
	global_load_dwordx4 v[220:223], v[6:7], off offset:2048
	global_load_dwordx4 v[224:227], v[4:5], off offset:3072
	global_load_dwordx4 v[228:231], v[6:7], off offset:3072
	v_mov_b32_e32 v248, v2
	v_mov_b32_e32 v249, 0
	v_lshlrev_b64 v[248:249], 12, v[248:249]
	v_lshl_add_u64 v[248:249], v[8:9], 0, v[248:249]
	global_load_dwordx4 v[232:235], v[248:249], off
	global_load_dwordx4 v[236:239], v[248:249], off offset:1024
	global_load_dwordx4 v[240:243], v[248:249], off offset:2048
	global_load_dwordx4 v[244:247], v[248:249], off offset:3072
	s_waitcnt vmcnt(0)
	s_branch .LBB0_473

.LBB0_473:
	v_ashrrev_i32_e32 v3, 31, v2
	v_lshlrev_b64 v[14:15], 12, v[2:3]
	v_lshl_add_u64 v[14:15], v[8:9], 0, v[14:15]
	s_waitcnt lgkmcnt(0)
	s_waitcnt vmcnt(8)
	v_mov_b64_e32 v[22:23], v[232:233]
	v_mov_b64_e32 v[24:25], v[234:235]
	v_mov_b64_e32 v[26:27], v[236:237]
	v_mov_b64_e32 v[28:29], v[238:239]
	v_mov_b64_e32 v[30:31], v[240:241]
	v_mov_b64_e32 v[32:33], v[242:243]
	v_mov_b64_e32 v[34:35], v[244:245]
	v_mov_b64_e32 v[36:37], v[246:247]
	v_add_u32_e32 v248, s12, v2
	v_min_i32_e32 v248, s16, v248
	v_mov_b32_e32 v249, 0
	v_lshlrev_b64 v[248:249], 12, v[248:249]
	v_lshl_add_u64 v[248:249], v[8:9], 0, v[248:249]
	global_load_dwordx4 v[232:235], v[248:249], off
	global_load_dwordx4 v[236:239], v[248:249], off offset:1024
	global_load_dwordx4 v[240:243], v[248:249], off offset:2048
	global_load_dwordx4 v[244:247], v[248:249], off offset:3072
	v_mov_b32_e32 v38, v22
	v_mov_b32_e32 v39, v26
	v_mov_b32_e32 v40, v23
	v_mov_b32_e32 v41, v27
	v_mov_b32_e32 v42, v24
	v_mov_b32_e32 v43, v28
	v_pk_add_f32 v[38:39], v[38:39], v[40:41]
	v_mov_b32_e32 v44, v25
	v_mov_b32_e32 v45, v29
	v_mov_b32_e32 v46, v30
	v_mov_b32_e32 v47, v34
	v_mov_b32_e32 v48, v31
	v_mov_b32_e32 v49, v35
	v_pk_add_f32 v[38:39], v[38:39], v[42:43]
	v_mov_b32_e32 v50, v32
	v_mov_b32_e32 v51, v36
	v_pk_add_f32 v[40:41], v[46:47], v[48:49]
	v_pk_add_f32 v[38:39], v[38:39], v[44:45]
	v_mov_b32_e32 v52, v33
	v_mov_b32_e32 v53, v37
	v_pk_add_f32 v[40:41], v[40:41], v[50:51]
	v_add_f32_e32 v38, 0, v38
	v_pk_add_f32 v[40:41], v[40:41], v[52:53]
	v_add_f32_e32 v38, v38, v39
	v_add_f32_e32 v38, v38, v40
	v_add_f32_e32 v38, v38, v41
	ds_bpermute_b32 v39, v1, v38
	s_waitcnt lgkmcnt(0)
	v_add_f32_e32 v38, v38, v39
	ds_bpermute_b32 v39, v16, v38
	s_waitcnt lgkmcnt(0)
	v_add_f32_e32 v38, v38, v39
	ds_bpermute_b32 v39, v17, v38
	s_waitcnt lgkmcnt(0)
	v_add_f32_e32 v38, v38, v39
	ds_bpermute_b32 v39, v18, v38
	s_waitcnt lgkmcnt(0)
	v_add_f32_e32 v38, v38, v39
	ds_bpermute_b32 v39, v19, v38
	s_waitcnt lgkmcnt(0)
	v_add_f32_e32 v46, v38, v39
	v_mov_b64_e32 v[38:39], v[200:201]
	v_mov_b64_e32 v[40:41], v[202:203]
	v_mov_b64_e32 v[42:43], v[204:205]
	v_mov_b64_e32 v[44:45], v[206:207]
	ds_bpermute_b32 v47, v20, v46
	s_waitcnt lgkmcnt(0)
	v_add_f32_e32 v46, v46, v47
	v_mul_f32_e32 v46, 0x3a800000, v46
	v_pk_add_f32 v[22:23], v[22:23], v[46:47] op_sel_hi:[1,0] neg_lo:[0,1] neg_hi:[0,1]
	v_pk_add_f32 v[48:49], v[26:27], v[46:47] op_sel_hi:[1,0] neg_lo:[0,1] neg_hi:[0,1]
	v_pk_add_f32 v[50:51], v[28:29], v[46:47] op_sel_hi:[1,0] neg_lo:[0,1] neg_hi:[0,1]
	v_pk_add_f32 v[52:53], v[30:31], v[46:47] op_sel_hi:[1,0] neg_lo:[0,1] neg_hi:[0,1]
	v_pk_add_f32 v[56:57], v[34:35], v[46:47] op_sel_hi:[1,0] neg_lo:[0,1] neg_hi:[0,1]
	v_mov_b32_e32 v28, v23
	v_mov_b32_e32 v29, v49
	v_pk_add_f32 v[24:25], v[24:25], v[46:47] op_sel_hi:[1,0] neg_lo:[0,1] neg_hi:[0,1]
	v_pk_add_f32 v[54:55], v[32:33], v[46:47] op_sel_hi:[1,0] neg_lo:[0,1] neg_hi:[0,1]
	v_pk_add_f32 v[46:47], v[36:37], v[46:47] op_sel_hi:[1,0] neg_lo:[0,1] neg_hi:[0,1]
	v_mov_b32_e32 v26, v22
	v_mov_b32_e32 v27, v48
	v_mov_b32_e32 v36, v57
	v_mov_b32_e32 v37, v53
	v_pk_mul_f32 v[28:29], v[28:29], v[28:29]
	v_mov_b32_e32 v30, v24
	v_mov_b32_e32 v31, v50
	v_mov_b32_e32 v34, v56
	v_mov_b32_e32 v35, v52
	v_pk_mul_f32 v[36:37], v[36:37], v[36:37]
	v_pk_fma_f32 v[26:27], v[26:27], v[26:27], v[28:29]
	v_mov_b32_e32 v32, v25
	v_mov_b32_e32 v33, v51
	v_mov_b32_e32 v58, v46
	v_mov_b32_e32 v59, v54
	v_pk_fma_f32 v[28:29], v[34:35], v[34:35], v[36:37]
	v_pk_fma_f32 v[26:27], v[30:31], v[30:31], v[26:27]
	v_mov_b32_e32 v60, v47
	v_mov_b32_e32 v61, v55
	v_pk_fma_f32 v[28:29], v[58:59], v[58:59], v[28:29]
	v_pk_fma_f32 v[26:27], v[32:33], v[32:33], v[26:27]
	v_pk_fma_f32 v[28:29], v[60:61], v[60:61], v[28:29]
	v_add_f32_e32 v26, v26, v27
	v_add_f32_e32 v26, v29, v26
	v_add_f32_e32 v26, v28, v26
	ds_bpermute_b32 v27, v1, v26
	s_waitcnt lgkmcnt(0)
	v_add_f32_e32 v26, v26, v27
	ds_bpermute_b32 v27, v16, v26
	s_waitcnt lgkmcnt(0)
	v_add_f32_e32 v26, v26, v27
	ds_bpermute_b32 v27, v17, v26
	s_waitcnt lgkmcnt(0)
	v_add_f32_e32 v26, v26, v27
	ds_bpermute_b32 v27, v18, v26
	s_waitcnt lgkmcnt(0)
	v_add_f32_e32 v26, v26, v27
	ds_bpermute_b32 v27, v19, v26
	s_waitcnt lgkmcnt(0)
	v_add_f32_e32 v26, v26, v27
	ds_bpermute_b32 v27, v20, v26
	s_waitcnt lgkmcnt(0)
	v_add_f32_e32 v26, v26, v27
	v_fmamk_f32 v26, v26, 0x3a800000, v21
	v_mul_f32_e32 v27, 0x4b800000, v26
	v_cmp_gt_f32_e32 vcc, s13, v26
	s_nop 1
	v_cndmask_b32_e32 v26, v26, v27, vcc
	v_rsq_f32_e32 v28, v26
	v_lshlrev_b64 v[26:27], 11, v[2:3]
	v_lshl_add_u64 v[58:59], v[10:11], 0, v[26:27]
	v_mul_f32_e32 v26, 0x45800000, v28
	v_cndmask_b32_e32 v60, v28, v26, vcc
	v_pk_mul_f32 v[22:23], v[22:23], v[60:61] op_sel_hi:[1,0]
	v_pk_mul_f32 v[24:25], v[24:25], v[60:61] op_sel_hi:[1,0]
	v_pk_fma_f32 v[22:23], v[38:39], v[22:23], v[42:43]
	v_pk_fma_f32 v[24:25], v[40:41], v[24:25], v[44:45]
	v_cvt_pk_bf16_f32 v26, v22, v23
	v_cvt_pk_bf16_f32 v27, v24, v25
	global_store_dwordx4 v[14:15], v[22:25], off
	v_mov_b64_e32 v[26:27], v[208:209]
	v_mov_b64_e32 v[28:29], v[210:211]
	s_nop 0
	v_mov_b64_e32 v[30:31], v[212:213]
	v_mov_b64_e32 v[32:33], v[214:215]
	v_pk_mul_f32 v[34:35], v[48:49], v[60:61] op_sel_hi:[1,0]
	v_pk_mul_f32 v[36:37], v[50:51], v[60:61] op_sel_hi:[1,0]
	v_pk_mul_f32 v[38:39], v[52:53], v[60:61] op_sel_hi:[1,0]
	v_pk_mul_f32 v[40:41], v[54:55], v[60:61] op_sel_hi:[1,0]
	v_pk_mul_f32 v[44:45], v[46:47], v[60:61] op_sel_hi:[1,0]
	v_max_f32_e64 v46, |v24|, |v25|
	v_pk_mul_f32 v[42:43], v[56:57], v[60:61] op_sel_hi:[1,0]
	v_max3_f32 v46, |v22|, |v23|, v46
	v_pk_fma_f32 v[26:27], v[26:27], v[34:35], v[30:31]
	v_pk_fma_f32 v[28:29], v[28:29], v[36:37], v[32:33]
	v_cvt_pk_bf16_f32 v30, v26, v27
	v_cvt_pk_bf16_f32 v31, v28, v29
	global_store_dwordx4 v[14:15], v[26:29], off offset:1024
	v_mov_b64_e32 v[30:31], v[216:217]
	v_mov_b64_e32 v[32:33], v[218:219]
	s_nop 0
	v_mov_b64_e32 v[34:35], v[220:221]
	v_mov_b64_e32 v[36:37], v[222:223]
	v_max_f32_e64 v47, |v28|, |v29|
	v_max3_f32 v47, |v26|, |v27|, v47
	v_max3_f32 v46, v46, 0, v47
	v_pk_fma_f32 v[30:31], v[38:39], v[30:31], v[34:35]
	v_pk_fma_f32 v[32:33], v[40:41], v[32:33], v[36:37]
	v_cvt_pk_bf16_f32 v34, v30, v31
	v_cvt_pk_bf16_f32 v35, v32, v33
	global_store_dwordx4 v[14:15], v[30:33], off offset:2048
	v_mov_b64_e32 v[34:35], v[224:225]
	v_mov_b64_e32 v[36:37], v[226:227]
	s_nop 0
	v_mov_b64_e32 v[38:39], v[228:229]
	v_mov_b64_e32 v[40:41], v[230:231]
	v_max_f32_e64 v47, |v32|, |v33|
	v_max3_f32 v47, |v30|, |v31|, v47
	v_pk_fma_f32 v[36:37], v[44:45], v[36:37], v[40:41]
	v_pk_fma_f32 v[34:35], v[42:43], v[34:35], v[38:39]
	v_max_f32_e64 v38, |v36|, |v37|
	v_max3_f32 v38, |v34|, |v35|, v38
	v_max3_f32 v38, v46, v47, v38
	ds_bpermute_b32 v39, v1, v38
	global_store_dwordx4 v[14:15], v[34:37], off offset:3072
	s_waitcnt lgkmcnt(0)
	v_max_f32_e32 v39, v39, v39
	v_max_f32_e32 v38, v38, v39
	ds_bpermute_b32 v39, v16, v38
	s_waitcnt lgkmcnt(0)
	v_max_f32_e32 v39, v39, v39
	v_max_f32_e32 v38, v38, v39
	ds_bpermute_b32 v39, v17, v38
	s_waitcnt lgkmcnt(0)
	v_max_f32_e32 v39, v39, v39
	v_max_f32_e32 v38, v38, v39
	ds_bpermute_b32 v39, v18, v38
	s_waitcnt lgkmcnt(0)
	v_max_f32_e32 v39, v39, v39
	v_max_f32_e32 v40, v38, v39
	ds_bpermute_b32 v41, v19, v40
	v_lshlrev_b64 v[38:39], 10, v[2:3]
	v_lshl_add_u64 v[38:39], v[12:13], 0, v[38:39]
	s_waitcnt lgkmcnt(0)
	v_max_f32_e32 v41, v41, v41
	v_max_f32_e32 v42, v40, v41
	ds_bpermute_b32 v43, v20, v42
	v_cvt_pk_bf16_f32 v40, v34, v35
	v_cvt_pk_bf16_f32 v41, v36, v37
	s_waitcnt lgkmcnt(0)
	v_max_f32_e32 v14, v43, v43
	v_max_f32_e32 v14, v42, v14
	v_div_scale_f32 v15, s[2:3], v14, v14, s14
	v_rcp_f32_e32 v42, v15
	v_div_scale_f32 v40, vcc, s14, v14, s14
	v_cmp_lt_f32_e64 s[6:7], 0, v14
	v_fma_f32 v41, -v15, v42, 1.0
	v_fmac_f32_e32 v42, v41, v42
	v_mul_f32_e32 v41, v40, v42
	v_fma_f32 v43, -v15, v41, v40
	v_fmac_f32_e32 v41, v43, v42
	v_fma_f32 v15, -v15, v41, v40
	v_div_fmas_f32 v15, v15, v42, v41
	v_div_fixup_f32 v15, v15, v14, s14
	v_cndmask_b32_e64 v15, 0, v15, s[6:7]
	v_mul_f32_e32 v22, v22, v15
	v_mul_f32_e32 v23, v23, v15
	v_mul_f32_e32 v24, v24, v15
	v_mul_f32_e32 v25, v25, v15
	v_mul_f32_e32 v26, v26, v15
	v_mul_f32_e32 v27, v27, v15
	v_mul_f32_e32 v28, v28, v15
	v_mul_f32_e32 v29, v29, v15
	v_rndne_f32_e32 v22, v22
	v_rndne_f32_e32 v23, v23
	v_rndne_f32_e32 v24, v24
	v_rndne_f32_e32 v25, v25
	v_rndne_f32_e32 v26, v26
	v_rndne_f32_e32 v27, v27
	v_mul_f32_e32 v30, v30, v15
	v_mul_f32_e32 v31, v31, v15
	v_mul_f32_e32 v32, v32, v15
	v_mul_f32_e32 v33, v33, v15
	v_mul_f32_e32 v34, v34, v15
	v_mul_f32_e32 v35, v35, v15
	v_mul_f32_e32 v36, v36, v15
	v_mul_f32_e32 v15, v37, v15
	v_rndne_f32_e32 v28, v28
	v_rndne_f32_e32 v29, v29
	v_add_f32_e32 v37, v22, v23
	v_add_f32_e32 v40, v24, v25
	v_cvt_i32_f32_e32 v22, v22
	v_cvt_i32_f32_e32 v23, v23
	v_cvt_i32_f32_e32 v25, v25
	v_add_f32_e32 v41, v26, v27
	v_cvt_i32_f32_e32 v27, v27
	v_rndne_f32_e32 v30, v30
	v_rndne_f32_e32 v31, v31
	v_rndne_f32_e32 v32, v32
	v_rndne_f32_e32 v33, v33
	v_cvt_i32_f32_sdwa v24, v24 dst_sel:WORD_1 dst_unused:UNUSED_PAD src0_sel:DWORD
	v_add_f32_e32 v42, v28, v29
	v_add_f32_e32 v37, v37, v40
	v_rndne_f32_e32 v34, v34
	v_rndne_f32_e32 v35, v35
	v_rndne_f32_e32 v36, v36
	v_rndne_f32_e32 v15, v15
	v_add_f32_e32 v43, v30, v31
	v_add_f32_e32 v44, v32, v33
	v_add_f32_e32 v40, v41, v42
	v_add_f32_e32 v37, 0, v37
	v_add_f32_e32 v45, v34, v35
	v_add_f32_e32 v46, v36, v15
	v_add_f32_e32 v41, v43, v44
	v_add_f32_e32 v37, v40, v37
	v_add_f32_e32 v42, v45, v46
	v_lshlrev_b32_e32 v23, 8, v23
	v_perm_b32 v22, v25, v22, s15
	v_lshlrev_b32_e32 v25, 8, v27
	v_add_f32_e32 v27, v41, v37
	v_cvt_i32_f32_e32 v26, v26
	v_cvt_i32_f32_sdwa v28, v28 dst_sel:WORD_1 dst_unused:UNUSED_PAD src0_sel:DWORD
	v_cvt_i32_f32_e32 v29, v29
	v_and_b32_e32 v24, 0xff0000, v24
	v_and_b32_e32 v23, 0xff00, v23
	v_add_f32_e32 v27, v42, v27
	v_or3_b32 v22, v22, v23, v24
	ds_bpermute_b32 v23, v1, v27
	v_and_b32_e32 v25, 0xff00, v25
	global_store_dword v[38:39], v22, off
	v_and_b32_e32 v22, 0xff0000, v28
	v_perm_b32 v24, v29, v26, s15
	v_or3_b32 v22, v24, v25, v22
	global_store_dword v[38:39], v22, off offset:256
	s_waitcnt lgkmcnt(0)
	v_add_f32_e32 v22, v27, v23
	ds_bpermute_b32 v23, v16, v22
	v_cvt_i32_f32_e32 v25, v31
	v_cvt_i32_f32_e32 v24, v30
	v_cvt_i32_f32_sdwa v26, v32 dst_sel:WORD_1 dst_unused:UNUSED_PAD src0_sel:DWORD
	v_cvt_i32_f32_e32 v27, v33
	s_waitcnt lgkmcnt(0)
	v_add_f32_e32 v22, v22, v23
	ds_bpermute_b32 v23, v17, v22
	v_lshlrev_b32_e32 v25, 8, v25
	v_and_b32_e32 v25, 0xff00, v25
	v_and_b32_e32 v26, 0xff0000, v26
	v_perm_b32 v24, v27, v24, s15
	s_waitcnt lgkmcnt(0)
	v_add_f32_e32 v22, v22, v23
	ds_bpermute_b32 v23, v18, v22
	v_or3_b32 v24, v24, v25, v26
	v_cvt_i32_f32_e32 v25, v35
	v_cvt_i32_f32_e32 v27, v15
	global_store_dword v[38:39], v24, off offset:512
	s_waitcnt lgkmcnt(0)
	v_add_f32_e32 v22, v22, v23
	ds_bpermute_b32 v23, v19, v22
	v_lshlrev_b32_e32 v15, 8, v25
	v_cvt_i32_f32_e32 v24, v34
	v_cvt_i32_f32_sdwa v26, v36 dst_sel:WORD_1 dst_unused:UNUSED_PAD src0_sel:DWORD
	v_and_b32_e32 v25, 0xff00, v15
	s_waitcnt lgkmcnt(0)
	v_add_f32_e32 v15, v22, v23
	ds_bpermute_b32 v22, v20, v15
	v_and_b32_e32 v23, 0xff0000, v26
	v_perm_b32 v24, v27, v24, s15
	v_or3_b32 v23, v24, v25, v23
	global_store_dword v[38:39], v23, off offset:768
	s_and_saveexec_b64 s[2:3], s[4:5]
	s_cbranch_execz .LBB0_472
	v_div_scale_f32 v23, s[18:19], s14, s14, v14
	v_rcp_f32_e32 v24, v23
	s_waitcnt lgkmcnt(0)
	v_add_f32_e32 v25, v15, v22
	v_fma_f32 v15, -v23, v24, 1.0
	v_fmac_f32_e32 v24, v15, v24
	v_div_scale_f32 v15, vcc, v14, s14, v14
	v_mul_f32_e32 v22, v15, v24
	v_fma_f32 v26, -v23, v22, v15
	v_fmac_f32_e32 v22, v26, v24
	v_fma_f32 v15, -v23, v22, v15
	v_div_fmas_f32 v15, v15, v24, v22
	v_div_fixup_f32 v14, v15, s14, v14
	v_cndmask_b32_e64 v24, 0, v14, s[6:7]
	v_lshlrev_b64 v[14:15], 2, v[2:3]
	v_lshl_add_u64 v[22:23], s[68:69], 0, v[14:15]
	v_lshl_add_u64 v[14:15], s[70:71], 0, v[14:15]
	global_store_dword v[22:23], v24, off
	global_store_dword v[14:15], v25, off
	s_branch .LBB0_472

.LBB0_841:
	v_lshrrev_b32_e32 v0, 6, v106
	v_lshl_add_u32 v0, s96, 2, v0
	s_mov_b32 s0, 0x8000
	v_cmp_gt_i32_e32 vcc, s0, v0
	s_and_saveexec_b64 s[0:1], vcc
	s_cbranch_execz .LBB0_846
	v_mbcnt_lo_u32_b32 v2, -1, 0
	v_mbcnt_hi_u32_b32 v2, -1, v2
	v_and_b32_e32 v3, 64, v2
	v_add_u32_e32 v3, 64, v3
	v_xor_b32_e32 v4, 32, v2
	v_cmp_lt_i32_e32 vcc, v4, v3
	v_readlane_b32 s12, v254, 24
	v_readlane_b32 s14, v254, 26
	v_cndmask_b32_e32 v4, v2, v4, vcc
	s_waitcnt vmcnt(18)
	v_lshlrev_b32_e32 v26, 2, v4
	v_xor_b32_e32 v4, 16, v2
	v_cmp_lt_i32_e32 vcc, v4, v3
	v_readlane_b32 s15, v254, 27
	s_add_u32 s2, s14, 0x2000
	v_cndmask_b32_e32 v4, v2, v4, vcc
	v_lshlrev_b32_e32 v27, 2, v4
	v_xor_b32_e32 v4, 8, v2
	v_cmp_lt_i32_e32 vcc, v4, v3
	s_addc_u32 s3, s15, 0
	v_and_b32_e32 v1, 63, v106
	v_cndmask_b32_e32 v4, v2, v4, vcc
	v_lshlrev_b32_e32 v28, 2, v4
	v_xor_b32_e32 v4, 4, v2
	v_cmp_lt_i32_e32 vcc, v4, v3
	v_readlane_b32 s13, v254, 25
	s_add_u32 s6, s12, 0x2000
	v_cndmask_b32_e32 v4, v2, v4, vcc
	v_lshlrev_b32_e32 v29, 2, v4
	v_xor_b32_e32 v4, 2, v2
	v_cmp_lt_i32_e32 vcc, v4, v3
	v_readlane_b32 s10, v254, 0
	v_mov_b32_e32 v23, 0
	v_cndmask_b32_e32 v4, v2, v4, vcc
	s_waitcnt vmcnt(16)
	v_lshlrev_b32_e32 v30, 2, v4
	v_xor_b32_e32 v4, 1, v2
	v_lshlrev_b32_e32 v18, 4, v1
	v_cmp_lt_i32_e32 vcc, v4, v3
	v_readlane_b32 s16, v254, 28
	v_readlane_b32 s17, v254, 29
	s_addc_u32 s7, s13, 0
	s_waitcnt lgkmcnt(0)
	v_lshlrev_b32_e32 v22, 2, v1
	v_readlane_b32 s11, v254, 1
	v_cndmask_b32_e32 v2, v2, v4, vcc
	v_mov_b32_e32 v19, v23
	v_or_b32_e32 v8, 0x400, v18
	v_mov_b32_e32 v9, v23
	v_or_b32_e32 v12, 0x800, v18
	v_mov_b32_e32 v13, v23
	v_or_b32_e32 v16, 0xc00, v18
	v_mov_b32_e32 v17, v23
	v_lshlrev_b32_e32 v20, 3, v1
	v_mov_b32_e32 v21, v23
	v_cmp_eq_u32_e64 s[4:5], 0, v1
	s_lshl_b32 s12, s10, 2
	v_lshlrev_b32_e32 v31, 2, v2
	v_lshl_add_u64 v[2:3], s[6:7], 0, v[18:19]
	v_lshl_add_u64 v[4:5], s[2:3], 0, v[18:19]
	v_lshl_add_u64 v[6:7], s[6:7], 0, v[8:9]
	v_lshl_add_u64 v[8:9], s[2:3], 0, v[8:9]
	v_lshl_add_u64 v[10:11], s[6:7], 0, v[12:13]
	v_lshl_add_u64 v[12:13], s[2:3], 0, v[12:13]
	v_lshl_add_u64 v[14:15], s[6:7], 0, v[16:17]
	v_lshl_add_u64 v[16:17], s[2:3], 0, v[16:17]
	v_lshl_add_u64 v[18:19], s[82:83], 0, v[18:19]
	v_lshl_add_u64 v[20:21], s[16:17], 0, v[20:21]
	v_lshl_add_u64 v[22:23], s[94:95], 0, v[22:23]
	s_mov_b64 s[10:11], 0
	v_mov_b32_e32 v32, 0x3727c5ac
	s_mov_b32 s13, 0x800000
	s_mov_b32 s14, 0x42fe0000
	s_mov_b32 s15, 0x40c0c00
	s_movk_i32 s16, 0x7fff
	v_readlane_b32 s18, v254, 30
	v_readlane_b32 s19, v254, 31
	v_readlane_b32 s20, v254, 32
	v_readlane_b32 s21, v254, 33
	v_readlane_b32 s22, v254, 34
	v_readlane_b32 s23, v254, 35
	v_readlane_b32 s24, v254, 36
	v_readlane_b32 s25, v254, 37
	v_readlane_b32 s26, v254, 38
	v_readlane_b32 s27, v254, 39
	global_load_dwordx4 v[200:203], v[2:3], off
	global_load_dwordx4 v[204:207], v[4:5], off
	global_load_dwordx4 v[208:211], v[6:7], off
	global_load_dwordx4 v[212:215], v[8:9], off
	global_load_dwordx4 v[216:219], v[10:11], off
	global_load_dwordx4 v[220:223], v[12:13], off
	global_load_dwordx4 v[224:227], v[14:15], off
	global_load_dwordx4 v[228:231], v[16:17], off
	v_mov_b32_e32 v248, v0
	v_mov_b32_e32 v249, 0
	v_lshlrev_b64 v[248:249], 12, v[248:249]
	v_lshl_add_u64 v[248:249], v[18:19], 0, v[248:249]
	global_load_dwordx4 v[232:235], v[248:249], off
	global_load_dwordx4 v[236:239], v[248:249], off offset:1024
	global_load_dwordx4 v[240:243], v[248:249], off offset:2048
	global_load_dwordx4 v[244:247], v[248:249], off offset:3072
	s_waitcnt vmcnt(0)
	s_branch .LBB0_844

.LBB0_844:
	v_ashrrev_i32_e32 v1, 31, v0
	v_lshlrev_b64 v[24:25], 12, v[0:1]
	v_lshl_add_u64 v[24:25], v[18:19], 0, v[24:25]
	s_waitcnt vmcnt(8)
	v_mov_b64_e32 v[34:35], v[232:233]
	v_mov_b64_e32 v[36:37], v[234:235]
	v_mov_b64_e32 v[38:39], v[236:237]
	v_mov_b64_e32 v[40:41], v[238:239]
	v_mov_b64_e32 v[42:43], v[240:241]
	v_mov_b64_e32 v[44:45], v[242:243]
	v_mov_b64_e32 v[46:47], v[244:245]
	v_mov_b64_e32 v[48:49], v[246:247]
	v_add_u32_e32 v248, s12, v0
	v_min_i32_e32 v248, s16, v248
	v_mov_b32_e32 v249, 0
	v_lshlrev_b64 v[248:249], 12, v[248:249]
	v_lshl_add_u64 v[248:249], v[18:19], 0, v[248:249]
	global_load_dwordx4 v[232:235], v[248:249], off
	global_load_dwordx4 v[236:239], v[248:249], off offset:1024
	global_load_dwordx4 v[240:243], v[248:249], off offset:2048
	global_load_dwordx4 v[244:247], v[248:249], off offset:3072
	v_mov_b32_e32 v50, v34
	v_mov_b32_e32 v51, v38
	v_mov_b32_e32 v52, v35
	v_mov_b32_e32 v53, v39
	v_mov_b32_e32 v54, v36
	v_mov_b32_e32 v55, v40
	v_pk_add_f32 v[50:51], v[50:51], v[52:53]
	v_mov_b32_e32 v56, v37
	v_mov_b32_e32 v57, v41
	v_mov_b32_e32 v58, v42
	v_mov_b32_e32 v59, v46
	v_mov_b32_e32 v60, v43
	v_mov_b32_e32 v61, v47
	v_pk_add_f32 v[50:51], v[50:51], v[54:55]
	v_mov_b32_e32 v62, v44
	v_mov_b32_e32 v63, v48
	v_pk_add_f32 v[52:53], v[58:59], v[60:61]
	v_pk_add_f32 v[50:51], v[50:51], v[56:57]
	v_mov_b32_e32 v64, v45
	v_mov_b32_e32 v65, v49
	v_pk_add_f32 v[52:53], v[52:53], v[62:63]
	s_waitcnt lgkmcnt(0)
	v_add_f32_e32 v33, 0, v50
	v_pk_add_f32 v[52:53], v[52:53], v[64:65]
	v_add_f32_e32 v33, v33, v51
	v_add_f32_e32 v33, v33, v52
	v_add_f32_e32 v33, v33, v53
	ds_bpermute_b32 v50, v26, v33
	s_waitcnt lgkmcnt(0)
	v_add_f32_e32 v33, v33, v50
	ds_bpermute_b32 v50, v27, v33
	s_waitcnt lgkmcnt(0)
	v_add_f32_e32 v33, v33, v50
	ds_bpermute_b32 v50, v28, v33
	s_waitcnt lgkmcnt(0)
	v_add_f32_e32 v33, v33, v50
	ds_bpermute_b32 v50, v29, v33
	s_waitcnt lgkmcnt(0)
	v_add_f32_e32 v33, v33, v50
	ds_bpermute_b32 v50, v30, v33
	s_waitcnt lgkmcnt(0)
	v_add_f32_e32 v33, v33, v50
	v_mov_b64_e32 v[50:51], v[200:201]
	v_mov_b64_e32 v[52:53], v[202:203]
	v_mov_b64_e32 v[54:55], v[204:205]
	v_mov_b64_e32 v[56:57], v[206:207]
	ds_bpermute_b32 v58, v31, v33
	s_waitcnt lgkmcnt(0)
	v_add_f32_e32 v33, v33, v58
	v_mul_f32_e32 v58, 0x3a800000, v33
	v_pk_add_f32 v[34:35], v[34:35], v[58:59] op_sel_hi:[1,0] neg_lo:[0,1] neg_hi:[0,1]
	v_pk_add_f32 v[60:61], v[38:39], v[58:59] op_sel_hi:[1,0] neg_lo:[0,1] neg_hi:[0,1]
	v_pk_add_f32 v[62:63], v[40:41], v[58:59] op_sel_hi:[1,0] neg_lo:[0,1] neg_hi:[0,1]
	v_pk_add_f32 v[64:65], v[42:43], v[58:59] op_sel_hi:[1,0] neg_lo:[0,1] neg_hi:[0,1]
	v_pk_add_f32 v[68:69], v[46:47], v[58:59] op_sel_hi:[1,0] neg_lo:[0,1] neg_hi:[0,1]
	v_mov_b32_e32 v40, v35
	v_mov_b32_e32 v41, v61
	v_pk_add_f32 v[36:37], v[36:37], v[58:59] op_sel_hi:[1,0] neg_lo:[0,1] neg_hi:[0,1]
	v_pk_add_f32 v[66:67], v[44:45], v[58:59] op_sel_hi:[1,0] neg_lo:[0,1] neg_hi:[0,1]
	v_pk_add_f32 v[58:59], v[48:49], v[58:59] op_sel_hi:[1,0] neg_lo:[0,1] neg_hi:[0,1]
	v_mov_b32_e32 v38, v34
	v_mov_b32_e32 v39, v60
	v_mov_b32_e32 v48, v69
	v_mov_b32_e32 v49, v65
	v_pk_mul_f32 v[40:41], v[40:41], v[40:41]
	v_mov_b32_e32 v42, v36
	v_mov_b32_e32 v43, v62
	v_mov_b32_e32 v46, v68
	v_mov_b32_e32 v47, v64
	v_pk_mul_f32 v[48:49], v[48:49], v[48:49]
	v_pk_fma_f32 v[38:39], v[38:39], v[38:39], v[40:41]
	v_mov_b32_e32 v44, v37
	v_mov_b32_e32 v45, v63
	v_mov_b32_e32 v70, v58
	v_mov_b32_e32 v71, v66
	v_pk_fma_f32 v[40:41], v[46:47], v[46:47], v[48:49]
	v_pk_fma_f32 v[38:39], v[42:43], v[42:43], v[38:39]
	v_mov_b32_e32 v72, v59
	v_mov_b32_e32 v73, v67
	v_pk_fma_f32 v[40:41], v[70:71], v[70:71], v[40:41]
	v_pk_fma_f32 v[38:39], v[44:45], v[44:45], v[38:39]
	v_pk_fma_f32 v[40:41], v[72:73], v[72:73], v[40:41]
	v_add_f32_e32 v33, v38, v39
	v_add_f32_e32 v33, v41, v33
	v_add_f32_e32 v33, v40, v33
	ds_bpermute_b32 v38, v26, v33
	s_waitcnt lgkmcnt(0)
	v_add_f32_e32 v33, v33, v38
	ds_bpermute_b32 v38, v27, v33
	s_waitcnt lgkmcnt(0)
	v_add_f32_e32 v33, v33, v38
	ds_bpermute_b32 v38, v28, v33
	s_waitcnt lgkmcnt(0)
	v_add_f32_e32 v33, v33, v38
	ds_bpermute_b32 v38, v29, v33
	s_waitcnt lgkmcnt(0)
	v_add_f32_e32 v33, v33, v38
	ds_bpermute_b32 v38, v30, v33
	s_waitcnt lgkmcnt(0)
	v_add_f32_e32 v33, v33, v38
	ds_bpermute_b32 v38, v31, v33
	s_waitcnt lgkmcnt(0)
	v_add_f32_e32 v33, v33, v38
	v_fmamk_f32 v33, v33, 0x3a800000, v32
	v_mul_f32_e32 v38, 0x4b800000, v33
	v_cmp_gt_f32_e32 vcc, s13, v33
	s_nop 1
	v_cndmask_b32_e32 v33, v33, v38, vcc
	v_rsq_f32_e32 v33, v33
	v_lshlrev_b64 v[38:39], 11, v[0:1]
	v_lshl_add_u64 v[70:71], v[20:21], 0, v[38:39]
	v_mul_f32_e32 v38, 0x45800000, v33
	v_cndmask_b32_e32 v72, v33, v38, vcc
	v_pk_mul_f32 v[34:35], v[34:35], v[72:73] op_sel_hi:[1,0]
	v_pk_mul_f32 v[36:37], v[36:37], v[72:73] op_sel_hi:[1,0]
	v_pk_fma_f32 v[34:35], v[50:51], v[34:35], v[54:55]
	v_pk_fma_f32 v[36:37], v[52:53], v[36:37], v[56:57]
	v_cvt_pk_bf16_f32 v38, v34, v35
	v_cvt_pk_bf16_f32 v39, v36, v37
	global_store_dwordx4 v[24:25], v[34:37], off
	v_mov_b64_e32 v[38:39], v[208:209]
	v_mov_b64_e32 v[40:41], v[210:211]
	s_nop 0
	v_mov_b64_e32 v[42:43], v[212:213]
	v_mov_b64_e32 v[44:45], v[214:215]
	v_pk_mul_f32 v[46:47], v[60:61], v[72:73] op_sel_hi:[1,0]
	v_pk_mul_f32 v[48:49], v[62:63], v[72:73] op_sel_hi:[1,0]
	v_pk_mul_f32 v[50:51], v[64:65], v[72:73] op_sel_hi:[1,0]
	v_pk_mul_f32 v[52:53], v[66:67], v[72:73] op_sel_hi:[1,0]
	v_pk_mul_f32 v[56:57], v[58:59], v[72:73] op_sel_hi:[1,0]
	v_max_f32_e64 v33, |v36|, |v37|
	v_pk_mul_f32 v[54:55], v[68:69], v[72:73] op_sel_hi:[1,0]
	v_max3_f32 v33, |v34|, |v35|, v33
	v_pk_fma_f32 v[38:39], v[38:39], v[46:47], v[42:43]
	v_pk_fma_f32 v[40:41], v[40:41], v[48:49], v[44:45]
	v_cvt_pk_bf16_f32 v42, v38, v39
	v_cvt_pk_bf16_f32 v43, v40, v41
	global_store_dwordx4 v[24:25], v[38:41], off offset:1024
	v_mov_b64_e32 v[42:43], v[216:217]
	v_mov_b64_e32 v[44:45], v[218:219]
	s_nop 0
	v_mov_b64_e32 v[46:47], v[220:221]
	v_mov_b64_e32 v[48:49], v[222:223]
	v_max_f32_e64 v58, |v40|, |v41|
	v_max3_f32 v58, |v38|, |v39|, v58
	v_max3_f32 v33, v33, 0, v58
	v_pk_fma_f32 v[42:43], v[50:51], v[42:43], v[46:47]
	v_pk_fma_f32 v[44:45], v[52:53], v[44:45], v[48:49]
	v_cvt_pk_bf16_f32 v46, v42, v43
	v_cvt_pk_bf16_f32 v47, v44, v45
	global_store_dwordx4 v[24:25], v[42:45], off offset:2048
	v_mov_b64_e32 v[46:47], v[224:225]
	v_mov_b64_e32 v[48:49], v[226:227]
	s_nop 0
	v_mov_b64_e32 v[50:51], v[228:229]
	v_mov_b64_e32 v[52:53], v[230:231]
	v_max_f32_e64 v58, |v44|, |v45|
	v_max3_f32 v58, |v42|, |v43|, v58
	v_pk_fma_f32 v[48:49], v[56:57], v[48:49], v[52:53]
	v_pk_fma_f32 v[46:47], v[54:55], v[46:47], v[50:51]
	v_max_f32_e64 v50, |v48|, |v49|
	v_max3_f32 v50, |v46|, |v47|, v50
	v_max3_f32 v33, v33, v58, v50
	ds_bpermute_b32 v50, v26, v33
	global_store_dwordx4 v[24:25], v[46:49], off offset:3072
	v_cvt_pk_bf16_f32 v53, v48, v49
	s_waitcnt lgkmcnt(0)
	v_max_f32_e32 v50, v50, v50
	v_max_f32_e32 v33, v33, v50
	ds_bpermute_b32 v50, v27, v33
	s_waitcnt lgkmcnt(0)
	v_max_f32_e32 v50, v50, v50
	v_max_f32_e32 v33, v33, v50
	ds_bpermute_b32 v50, v28, v33
	s_waitcnt lgkmcnt(0)
	v_max_f32_e32 v50, v50, v50
	v_max_f32_e32 v33, v33, v50
	ds_bpermute_b32 v50, v29, v33
	s_waitcnt lgkmcnt(0)
	v_max_f32_e32 v50, v50, v50
	v_max_f32_e32 v33, v33, v50
	ds_bpermute_b32 v52, v30, v33
	v_lshlrev_b64 v[50:51], 10, v[0:1]
	v_lshl_add_u64 v[50:51], v[22:23], 0, v[50:51]
	s_waitcnt lgkmcnt(0)
	v_max_f32_e32 v52, v52, v52
	v_max_f32_e32 v33, v33, v52
	ds_bpermute_b32 v54, v31, v33
	v_cvt_pk_bf16_f32 v52, v46, v47
	s_waitcnt lgkmcnt(0)
	v_max_f32_e32 v24, v54, v54
	v_max_f32_e32 v24, v33, v24
	v_div_scale_f32 v25, s[2:3], v24, v24, s14
	v_rcp_f32_e32 v33, v25
	v_div_scale_f32 v52, vcc, s14, v24, s14
	v_cmp_lt_f32_e64 s[6:7], 0, v24
	v_fma_f32 v53, -v25, v33, 1.0
	v_fmac_f32_e32 v33, v53, v33
	v_mul_f32_e32 v53, v52, v33
	v_fma_f32 v54, -v25, v53, v52
	v_fmac_f32_e32 v53, v54, v33
	v_fma_f32 v25, -v25, v53, v52
	v_div_fmas_f32 v25, v25, v33, v53
	v_div_fixup_f32 v25, v25, v24, s14
	v_cndmask_b32_e64 v25, 0, v25, s[6:7]
	v_mul_f32_e32 v33, v34, v25
	v_mul_f32_e32 v34, v35, v25
	v_mul_f32_e32 v35, v36, v25
	v_mul_f32_e32 v36, v37, v25
	v_mul_f32_e32 v37, v38, v25
	v_mul_f32_e32 v38, v39, v25
	v_mul_f32_e32 v39, v40, v25
	v_mul_f32_e32 v40, v41, v25
	v_rndne_f32_e32 v33, v33
	v_rndne_f32_e32 v34, v34
	v_rndne_f32_e32 v35, v35
	v_rndne_f32_e32 v36, v36
	v_rndne_f32_e32 v37, v37
	v_rndne_f32_e32 v38, v38
	v_mul_f32_e32 v41, v42, v25
	v_mul_f32_e32 v42, v43, v25
	v_mul_f32_e32 v43, v44, v25
	v_mul_f32_e32 v44, v45, v25
	v_mul_f32_e32 v45, v46, v25
	v_mul_f32_e32 v46, v47, v25
	v_mul_f32_e32 v47, v48, v25
	v_mul_f32_e32 v25, v49, v25
	v_rndne_f32_e32 v39, v39
	v_rndne_f32_e32 v40, v40
	v_add_f32_e32 v48, v33, v34
	v_add_f32_e32 v49, v35, v36
	v_cvt_i32_f32_e32 v33, v33
	v_cvt_i32_f32_e32 v34, v34
	v_cvt_i32_f32_e32 v36, v36
	v_add_f32_e32 v52, v37, v38
	v_cvt_i32_f32_e32 v38, v38
	v_rndne_f32_e32 v41, v41
	v_rndne_f32_e32 v42, v42
	v_rndne_f32_e32 v43, v43
	v_rndne_f32_e32 v44, v44
	v_cvt_i32_f32_sdwa v35, v35 dst_sel:WORD_1 dst_unused:UNUSED_PAD src0_sel:DWORD
	v_add_f32_e32 v53, v39, v40
	v_add_f32_e32 v48, v48, v49
	v_rndne_f32_e32 v45, v45
	v_rndne_f32_e32 v46, v46
	v_rndne_f32_e32 v47, v47
	v_rndne_f32_e32 v25, v25
	v_add_f32_e32 v54, v41, v42
	v_add_f32_e32 v55, v43, v44
	v_add_f32_e32 v49, v52, v53
	v_add_f32_e32 v48, 0, v48
	v_add_f32_e32 v56, v45, v46
	v_add_f32_e32 v57, v47, v25
	v_add_f32_e32 v52, v54, v55
	v_add_f32_e32 v48, v49, v48
	v_add_f32_e32 v53, v56, v57
	v_lshlrev_b32_e32 v34, 8, v34
	v_perm_b32 v33, v36, v33, s15
	v_lshlrev_b32_e32 v36, 8, v38
	v_add_f32_e32 v38, v52, v48
	v_cvt_i32_f32_e32 v37, v37
	v_cvt_i32_f32_sdwa v39, v39 dst_sel:WORD_1 dst_unused:UNUSED_PAD src0_sel:DWORD
	v_cvt_i32_f32_e32 v40, v40
	v_and_b32_e32 v35, 0xff0000, v35
	v_and_b32_e32 v34, 0xff00, v34
	v_add_f32_e32 v38, v53, v38
	v_or3_b32 v33, v33, v34, v35
	ds_bpermute_b32 v34, v26, v38
	v_and_b32_e32 v36, 0xff00, v36
	global_store_dword v[50:51], v33, off
	v_and_b32_e32 v33, 0xff0000, v39
	v_perm_b32 v35, v40, v37, s15
	v_or3_b32 v33, v35, v36, v33
	global_store_dword v[50:51], v33, off offset:256
	s_waitcnt lgkmcnt(0)
	v_add_f32_e32 v33, v38, v34
	ds_bpermute_b32 v34, v27, v33
	v_cvt_i32_f32_e32 v36, v42
	v_cvt_i32_f32_e32 v35, v41
	v_cvt_i32_f32_sdwa v37, v43 dst_sel:WORD_1 dst_unused:UNUSED_PAD src0_sel:DWORD
	v_cvt_i32_f32_e32 v38, v44
	s_waitcnt lgkmcnt(0)
	v_add_f32_e32 v33, v33, v34
	ds_bpermute_b32 v34, v28, v33
	v_lshlrev_b32_e32 v36, 8, v36
	v_and_b32_e32 v36, 0xff00, v36
	v_and_b32_e32 v37, 0xff0000, v37
	v_perm_b32 v35, v38, v35, s15
	s_waitcnt lgkmcnt(0)
	v_add_f32_e32 v33, v33, v34
	ds_bpermute_b32 v34, v29, v33
	v_or3_b32 v35, v35, v36, v37
	v_cvt_i32_f32_e32 v36, v46
	v_cvt_i32_f32_e32 v38, v25
	global_store_dword v[50:51], v35, off offset:512
	s_waitcnt lgkmcnt(0)
	v_add_f32_e32 v33, v33, v34
	ds_bpermute_b32 v34, v30, v33
	v_lshlrev_b32_e32 v25, 8, v36
	v_cvt_i32_f32_e32 v35, v45
	v_cvt_i32_f32_sdwa v37, v47 dst_sel:WORD_1 dst_unused:UNUSED_PAD src0_sel:DWORD
	v_and_b32_e32 v36, 0xff00, v25
	s_waitcnt lgkmcnt(0)
	v_add_f32_e32 v25, v33, v34
	ds_bpermute_b32 v33, v31, v25
	v_and_b32_e32 v34, 0xff0000, v37
	v_perm_b32 v35, v38, v35, s15
	v_or3_b32 v34, v35, v36, v34
	global_store_dword v[50:51], v34, off offset:768
	s_and_saveexec_b64 s[2:3], s[4:5]
	s_cbranch_execz .LBB0_843
	v_div_scale_f32 v34, s[18:19], s14, s14, v24
	v_rcp_f32_e32 v35, v34
	s_waitcnt lgkmcnt(0)
	v_add_f32_e32 v33, v25, v33
	v_fma_f32 v25, -v34, v35, 1.0
	v_fmac_f32_e32 v35, v25, v35
	v_div_scale_f32 v25, vcc, v24, s14, v24
	v_mul_f32_e32 v36, v25, v35
	v_fma_f32 v37, -v34, v36, v25
	v_fmac_f32_e32 v36, v37, v35
	v_fma_f32 v25, -v34, v36, v25
	v_div_fmas_f32 v25, v25, v35, v36
	v_div_fixup_f32 v24, v25, s14, v24
	v_cndmask_b32_e64 v36, 0, v24, s[6:7]
	v_lshlrev_b64 v[24:25], 2, v[0:1]
	v_lshl_add_u64 v[34:35], s[68:69], 0, v[24:25]
	v_lshl_add_u64 v[24:25], s[70:71], 0, v[24:25]
	global_store_dword v[34:35], v36, off
	global_store_dword v[24:25], v33, off
	s_branch .LBB0_843
